# v022 plus write-through (sc1) stores for the FFN-up SwiGLU epilogue output H (no L2 allocation)
# speedup vs baseline: 1.0053x; 1.0053x over previous
; DI unsigned pk2(float lo, float hi) { f32x2 v = {lo, hi}; return __builtin_bit_cast(unsigned, __builtin_convertvector(v, bf2_t)); }
; DI f32x2 swiglu_pk(f32x2 g, f32x2 u) {
;     const f32x2 t = g * (-1.44269504089f);
;     f32x2 e; e.x = __builtin_amdgcn_exp2f(t.x); e.y = __builtin_amdgcn_exp2f(t.y);
;     const f32x2 d = e + 1.0f;
;     f32x2 r; r.x = __builtin_amdgcn_rcpf(d.x); r.y = __builtin_amdgcn_rcpf(d.y);
;     return (g * r) * u;
; }
;     DI void operator()(const f32x4 (&acc)[2][2][4][2], const Unit& u, int wr, int wc, int fr, int fq) const {
;         const int row0 = u.pm * BM + wr * 64 + fr, col0 = u.pn * HALF + wc * 32 + 8 * fq;
; #pragma unroll
;         for (int ai = 0; ai < 2; ++ai)
; #pragma unroll
;             for (int m = 0; m < 4; ++m) {
;                 bf16_t* rowp = H + (size_t)(row0 + ai * HALF + m * 16) * ldh + col0;
;                 const f32x4 g0 = acc[ai][0][m][0], g1 = acc[ai][0][m][1], u0 = acc[ai][1][m][0], u1 = acc[ai][1][m][1];
;                 const f32x2 ha = swiglu_pk((f32x2){g0[0], g0[1]}, (f32x2){u0[0], u0[1]}), hb = swiglu_pk((f32x2){g0[2], g0[3]}, (f32x2){u0[2], u0[3]});
;                 const f32x2 hc = swiglu_pk((f32x2){g1[0], g1[1]}, (f32x2){u1[0], u1[1]}), hd = swiglu_pk((f32x2){g1[2], g1[3]}, (f32x2){u1[2], u1[3]});
;                 u32x4 w; w.x = pk2(ha.x, ha.y); w.y = pk2(hb.x, hb.y); w.z = pk2(hc.x, hc.y); w.w = pk2(hd.x, hd.y);
;                 *(u32x4*)rowp = w;
;             }
;     }
.LBB0_243:
	v_pk_mul_f32 v[152:153], v[126:127], s[30:31] op_sel_hi:[1,0]
	v_lshl_or_b32 v142, s50, 7, v146
	v_exp_f32_e32 v152, v152
	v_exp_f32_e32 v153, v153
	v_lshl_add_u32 v148, s52, 8, v144
	v_ashrrev_i32_e32 v143, 31, v142
	v_mov_b64_e32 v[140:141], s[80:81]
	v_pk_add_f32 v[152:153], v[152:153], 1.0 op_sel_hi:[1,0]
	v_mad_i64_i32 v[150:151], s[20:21], v148, s15, v[140:141]
	v_rcp_f32_e32 v152, v152
	v_rcp_f32_e32 v153, v153
	v_lshlrev_b64 v[142:143], 1, v[142:143]
	v_lshl_add_u64 v[150:151], v[150:151], 0, v[142:143]
	s_andn2_b64 vcc, exec, s[40:41]
	v_pk_mul_f32 v[126:127], v[126:127], v[152:153]
	s_nop 0
	v_pk_mul_f32 v[122:123], v[126:127], v[122:123]
	v_pk_mul_f32 v[126:127], v[128:129], s[30:31] op_sel_hi:[1,0]
	s_nop 0
	v_exp_f32_e32 v126, v126
	v_exp_f32_e32 v127, v127
	s_nop 0
	v_pk_add_f32 v[126:127], v[126:127], 1.0 op_sel_hi:[1,0]
	s_nop 0
	v_rcp_f32_e32 v126, v126
	v_rcp_f32_e32 v127, v127
	s_nop 0
	v_pk_mul_f32 v[126:127], v[128:129], v[126:127]
	s_nop 0
	v_pk_mul_f32 v[124:125], v[126:127], v[124:125]
	v_pk_mul_f32 v[126:127], v[118:119], s[30:31] op_sel_hi:[1,0]
	s_nop 0
	v_exp_f32_e32 v126, v126
	v_exp_f32_e32 v127, v127
	s_nop 0
	v_pk_add_f32 v[126:127], v[126:127], 1.0 op_sel_hi:[1,0]
	s_nop 0
	v_rcp_f32_e32 v126, v126
	v_rcp_f32_e32 v127, v127
	s_nop 0
	v_pk_mul_f32 v[118:119], v[118:119], v[126:127]
	s_nop 0
	v_pk_mul_f32 v[118:119], v[118:119], v[114:115]
	v_pk_mul_f32 v[114:115], v[120:121], s[30:31] op_sel_hi:[1,0]
	s_nop 0
	v_exp_f32_e32 v114, v114
	v_exp_f32_e32 v115, v115
	s_nop 0
	v_pk_add_f32 v[114:115], v[114:115], 1.0 op_sel_hi:[1,0]
	s_nop 0
	v_rcp_f32_e32 v114, v114
	v_rcp_f32_e32 v115, v115
	s_nop 0
	v_pk_mul_f32 v[114:115], v[120:121], v[114:115]
	s_nop 0
	v_pk_mul_f32 v[120:121], v[114:115], v[116:117]
	v_cvt_pk_bf16_f32 v114, v122, v123
	v_cvt_pk_bf16_f32 v115, v124, v125
	v_cvt_pk_bf16_f32 v116, v118, v119
	v_cvt_pk_bf16_f32 v117, v120, v121
	global_store_dwordx4 v[150:151], v[114:117], off sc1
	s_nop 1
	v_pk_mul_f32 v[116:117], v[110:111], s[30:31] op_sel_hi:[1,0]
	v_or_b32_e32 v114, 16, v148
	v_exp_f32_e32 v116, v116
	v_exp_f32_e32 v117, v117
	v_mad_i64_i32 v[114:115], s[20:21], v114, s15, v[140:141]
	v_lshl_add_u64 v[114:115], v[114:115], 0, v[142:143]
	v_pk_add_f32 v[116:117], v[116:117], 1.0 op_sel_hi:[1,0]
	s_nop 0
	v_rcp_f32_e32 v116, v116
	v_rcp_f32_e32 v117, v117
	s_nop 0
	v_pk_mul_f32 v[110:111], v[110:111], v[116:117]
	s_nop 0
	v_pk_mul_f32 v[106:107], v[110:111], v[106:107]
	v_pk_mul_f32 v[110:111], v[112:113], s[30:31] op_sel_hi:[1,0]
	s_nop 0
	v_exp_f32_e32 v110, v110
	v_exp_f32_e32 v111, v111
	s_nop 0
	v_pk_add_f32 v[110:111], v[110:111], 1.0 op_sel_hi:[1,0]
	s_nop 0
	v_rcp_f32_e32 v110, v110
	v_rcp_f32_e32 v111, v111
	s_nop 0
	v_pk_mul_f32 v[110:111], v[112:113], v[110:111]
	s_nop 0
	v_pk_mul_f32 v[108:109], v[110:111], v[108:109]
	v_pk_mul_f32 v[110:111], v[102:103], s[30:31] op_sel_hi:[1,0]
	s_nop 0
	v_exp_f32_e32 v110, v110
	v_exp_f32_e32 v111, v111
	s_nop 0
	v_pk_add_f32 v[110:111], v[110:111], 1.0 op_sel_hi:[1,0]
	s_nop 0
	v_rcp_f32_e32 v110, v110
	v_rcp_f32_e32 v111, v111
	s_nop 0
	v_pk_mul_f32 v[102:103], v[102:103], v[110:111]
	s_nop 0
	v_pk_mul_f32 v[102:103], v[102:103], v[98:99]
	v_pk_mul_f32 v[98:99], v[104:105], s[30:31] op_sel_hi:[1,0]
	s_nop 0
	v_exp_f32_e32 v98, v98
	v_exp_f32_e32 v99, v99
	s_nop 0
	v_pk_add_f32 v[98:99], v[98:99], 1.0 op_sel_hi:[1,0]
	s_nop 0
	v_rcp_f32_e32 v98, v98
	v_rcp_f32_e32 v99, v99
	s_nop 0
	v_pk_mul_f32 v[98:99], v[104:105], v[98:99]
	s_nop 0
	v_pk_mul_f32 v[104:105], v[98:99], v[100:101]
	v_cvt_pk_bf16_f32 v98, v106, v107
	v_cvt_pk_bf16_f32 v99, v108, v109
	v_cvt_pk_bf16_f32 v100, v102, v103
	v_cvt_pk_bf16_f32 v101, v104, v105
	global_store_dwordx4 v[114:115], v[98:101], off sc1
	s_nop 1
	v_pk_mul_f32 v[100:101], v[92:93], s[30:31] op_sel_hi:[1,0]
	v_or_b32_e32 v98, 32, v148
	v_exp_f32_e32 v100, v100
	v_exp_f32_e32 v101, v101
	v_mad_i64_i32 v[98:99], s[20:21], v98, s15, v[140:141]
	v_lshl_add_u64 v[98:99], v[98:99], 0, v[142:143]
	v_pk_add_f32 v[100:101], v[100:101], 1.0 op_sel_hi:[1,0]
	s_nop 0
	v_rcp_f32_e32 v100, v100
	v_rcp_f32_e32 v101, v101
	s_nop 0
	v_pk_mul_f32 v[92:93], v[92:93], v[100:101]
	s_nop 0
	v_pk_mul_f32 v[88:89], v[92:93], v[88:89]
	v_pk_mul_f32 v[92:93], v[94:95], s[30:31] op_sel_hi:[1,0]
	s_nop 0
	v_exp_f32_e32 v92, v92
	v_exp_f32_e32 v93, v93
	s_nop 0
	v_pk_add_f32 v[92:93], v[92:93], 1.0 op_sel_hi:[1,0]
	s_nop 0
	v_rcp_f32_e32 v92, v92
	v_rcp_f32_e32 v93, v93
	s_nop 0
	v_pk_mul_f32 v[92:93], v[94:95], v[92:93]
	s_nop 0
	v_pk_mul_f32 v[90:91], v[92:93], v[90:91]
	v_pk_mul_f32 v[92:93], v[84:85], s[30:31] op_sel_hi:[1,0]
	s_nop 0
	v_exp_f32_e32 v92, v92
	v_exp_f32_e32 v93, v93
	s_nop 0
	v_pk_add_f32 v[92:93], v[92:93], 1.0 op_sel_hi:[1,0]
	s_nop 0
	v_rcp_f32_e32 v92, v92
	v_rcp_f32_e32 v93, v93
	s_nop 0
	v_pk_mul_f32 v[84:85], v[84:85], v[92:93]
	s_nop 0
	v_pk_mul_f32 v[84:85], v[84:85], v[80:81]
	v_pk_mul_f32 v[80:81], v[86:87], s[30:31] op_sel_hi:[1,0]
	s_nop 0
	v_exp_f32_e32 v80, v80
	v_exp_f32_e32 v81, v81
	s_nop 0
	v_pk_add_f32 v[80:81], v[80:81], 1.0 op_sel_hi:[1,0]
	s_nop 0
	v_rcp_f32_e32 v80, v80
	v_rcp_f32_e32 v81, v81
	s_nop 0
	v_pk_mul_f32 v[80:81], v[86:87], v[80:81]
	s_nop 0
	v_pk_mul_f32 v[86:87], v[80:81], v[82:83]
	v_cvt_pk_bf16_f32 v80, v88, v89
	v_cvt_pk_bf16_f32 v81, v90, v91
	v_cvt_pk_bf16_f32 v82, v84, v85
	v_cvt_pk_bf16_f32 v83, v86, v87
	global_store_dwordx4 v[98:99], v[80:83], off sc1
	s_nop 1
	v_pk_mul_f32 v[82:83], v[76:77], s[30:31] op_sel_hi:[1,0]
	v_or_b32_e32 v80, 48, v148
	v_exp_f32_e32 v82, v82
	v_exp_f32_e32 v83, v83
	v_mad_i64_i32 v[80:81], s[20:21], v80, s15, v[140:141]
; DI unsigned pk2(float lo, float hi) { f32x2 v = {lo, hi}; return __builtin_bit_cast(unsigned, __builtin_convertvector(v, bf2_t)); }
; DI f32x2 swiglu_pk(f32x2 g, f32x2 u) {
;     const f32x2 t = g * (-1.44269504089f);
;     f32x2 e; e.x = __builtin_amdgcn_exp2f(t.x); e.y = __builtin_amdgcn_exp2f(t.y);
;     const f32x2 d = e + 1.0f;
;     f32x2 r; r.x = __builtin_amdgcn_rcpf(d.x); r.y = __builtin_amdgcn_rcpf(d.y);
;     return (g * r) * u;
; }
;     DI void operator()(const f32x4 (&acc)[2][2][4][2], const Unit& u, int wr, int wc, int fr, int fq) const {
;         const int row0 = u.pm * BM + wr * 64 + fr, col0 = u.pn * HALF + wc * 32 + 8 * fq;
; #pragma unroll
;         for (int ai = 0; ai < 2; ++ai)
; #pragma unroll
;             for (int m = 0; m < 4; ++m) {
;                 bf16_t* rowp = H + (size_t)(row0 + ai * HALF + m * 16) * ldh + col0;
;                 const f32x4 g0 = acc[ai][0][m][0], g1 = acc[ai][0][m][1], u0 = acc[ai][1][m][0], u1 = acc[ai][1][m][1];
;                 const f32x2 ha = swiglu_pk((f32x2){g0[0], g0[1]}, (f32x2){u0[0], u0[1]}), hb = swiglu_pk((f32x2){g0[2], g0[3]}, (f32x2){u0[2], u0[3]});
;                 const f32x2 hc = swiglu_pk((f32x2){g1[0], g1[1]}, (f32x2){u1[0], u1[1]}), hd = swiglu_pk((f32x2){g1[2], g1[3]}, (f32x2){u1[2], u1[3]});
;                 u32x4 w; w.x = pk2(ha.x, ha.y); w.y = pk2(hb.x, hb.y); w.z = pk2(hc.x, hc.y); w.w = pk2(hd.x, hd.y);
;                 *(u32x4*)rowp = w;
;             }
;     }
	v_lshl_add_u64 v[80:81], v[80:81], 0, v[142:143]
	v_pk_add_f32 v[82:83], v[82:83], 1.0 op_sel_hi:[1,0]
	s_nop 0
	v_rcp_f32_e32 v82, v82
	v_rcp_f32_e32 v83, v83
	s_nop 0
	v_pk_mul_f32 v[76:77], v[76:77], v[82:83]
	s_nop 0
	v_pk_mul_f32 v[72:73], v[76:77], v[72:73]
	v_pk_mul_f32 v[76:77], v[78:79], s[30:31] op_sel_hi:[1,0]
	s_nop 0
	v_exp_f32_e32 v76, v76
	v_exp_f32_e32 v77, v77
	s_nop 0
	v_pk_add_f32 v[76:77], v[76:77], 1.0 op_sel_hi:[1,0]
	s_nop 0
	v_rcp_f32_e32 v76, v76
	v_rcp_f32_e32 v77, v77
	s_nop 0
	v_pk_mul_f32 v[76:77], v[78:79], v[76:77]
	s_nop 0
	v_pk_mul_f32 v[74:75], v[76:77], v[74:75]
	v_pk_mul_f32 v[76:77], v[68:69], s[30:31] op_sel_hi:[1,0]
	s_nop 0
	v_exp_f32_e32 v76, v76
	v_exp_f32_e32 v77, v77
	s_nop 0
	v_pk_add_f32 v[76:77], v[76:77], 1.0 op_sel_hi:[1,0]
	s_nop 0
	v_rcp_f32_e32 v76, v76
	v_rcp_f32_e32 v77, v77
	s_nop 0
	v_pk_mul_f32 v[68:69], v[68:69], v[76:77]
	s_nop 0
	v_pk_mul_f32 v[68:69], v[68:69], v[64:65]
	v_pk_mul_f32 v[64:65], v[70:71], s[30:31] op_sel_hi:[1,0]
	s_nop 0
	v_exp_f32_e32 v64, v64
	v_exp_f32_e32 v65, v65
	s_nop 0
	v_pk_add_f32 v[64:65], v[64:65], 1.0 op_sel_hi:[1,0]
	s_nop 0
	v_rcp_f32_e32 v64, v64
	v_rcp_f32_e32 v65, v65
	s_nop 0
	v_pk_mul_f32 v[64:65], v[70:71], v[64:65]
	s_nop 0
	v_pk_mul_f32 v[70:71], v[64:65], v[66:67]
	v_cvt_pk_bf16_f32 v64, v72, v73
	v_cvt_pk_bf16_f32 v65, v74, v75
	v_cvt_pk_bf16_f32 v66, v68, v69
	v_cvt_pk_bf16_f32 v67, v70, v71
	global_store_dwordx4 v[80:81], v[64:67], off sc1
	s_nop 1
	v_pk_mul_f32 v[66:67], v[60:61], s[30:31] op_sel_hi:[1,0]
	v_add_u32_e32 v64, 0x80, v148
	v_exp_f32_e32 v66, v66
	v_exp_f32_e32 v67, v67
	v_mad_i64_i32 v[64:65], s[20:21], v64, s15, v[140:141]
	v_lshl_add_u64 v[64:65], v[64:65], 0, v[142:143]
	v_pk_add_f32 v[66:67], v[66:67], 1.0 op_sel_hi:[1,0]
	s_nop 0
	v_rcp_f32_e32 v66, v66
	v_rcp_f32_e32 v67, v67
	s_nop 0
	v_pk_mul_f32 v[60:61], v[60:61], v[66:67]
	s_nop 0
	v_pk_mul_f32 v[56:57], v[60:61], v[56:57]
	v_pk_mul_f32 v[60:61], v[62:63], s[30:31] op_sel_hi:[1,0]
	s_nop 0
	v_exp_f32_e32 v60, v60
	v_exp_f32_e32 v61, v61
	s_nop 0
	v_pk_add_f32 v[60:61], v[60:61], 1.0 op_sel_hi:[1,0]
	s_nop 0
	v_rcp_f32_e32 v60, v60
	v_rcp_f32_e32 v61, v61
	s_nop 0
	v_pk_mul_f32 v[60:61], v[62:63], v[60:61]
	s_nop 0
	v_pk_mul_f32 v[58:59], v[60:61], v[58:59]
	v_pk_mul_f32 v[60:61], v[52:53], s[30:31] op_sel_hi:[1,0]
	s_nop 0
	v_exp_f32_e32 v60, v60
	v_exp_f32_e32 v61, v61
	s_nop 0
	v_pk_add_f32 v[60:61], v[60:61], 1.0 op_sel_hi:[1,0]
	s_nop 0
	v_rcp_f32_e32 v60, v60
	v_rcp_f32_e32 v61, v61
	s_nop 0
	v_pk_mul_f32 v[52:53], v[52:53], v[60:61]
	s_nop 0
	v_pk_mul_f32 v[52:53], v[52:53], v[48:49]
	v_pk_mul_f32 v[48:49], v[54:55], s[30:31] op_sel_hi:[1,0]
	s_nop 0
	v_exp_f32_e32 v48, v48
	v_exp_f32_e32 v49, v49
	s_nop 0
	v_pk_add_f32 v[48:49], v[48:49], 1.0 op_sel_hi:[1,0]
	s_nop 0
	v_rcp_f32_e32 v48, v48
	v_rcp_f32_e32 v49, v49
	s_nop 0
	v_pk_mul_f32 v[48:49], v[54:55], v[48:49]
	s_nop 0
	v_pk_mul_f32 v[54:55], v[48:49], v[50:51]
	v_cvt_pk_bf16_f32 v48, v56, v57
	v_cvt_pk_bf16_f32 v49, v58, v59
	v_cvt_pk_bf16_f32 v50, v52, v53
	v_cvt_pk_bf16_f32 v51, v54, v55
	global_store_dwordx4 v[64:65], v[48:51], off sc1
	s_nop 1
	v_pk_mul_f32 v[50:51], v[44:45], s[30:31] op_sel_hi:[1,0]
	v_add_u32_e32 v48, 0x90, v148
	v_exp_f32_e32 v50, v50
	v_exp_f32_e32 v51, v51
	v_mad_i64_i32 v[48:49], s[20:21], v48, s15, v[140:141]
	v_lshl_add_u64 v[48:49], v[48:49], 0, v[142:143]
	v_pk_add_f32 v[50:51], v[50:51], 1.0 op_sel_hi:[1,0]
	s_nop 0
	v_rcp_f32_e32 v50, v50
	v_rcp_f32_e32 v51, v51
	s_nop 0
	v_pk_mul_f32 v[44:45], v[44:45], v[50:51]
	s_nop 0
	v_pk_mul_f32 v[40:41], v[44:45], v[40:41]
	v_pk_mul_f32 v[44:45], v[46:47], s[30:31] op_sel_hi:[1,0]
	s_nop 0
	v_exp_f32_e32 v44, v44
	v_exp_f32_e32 v45, v45
	s_nop 0
	v_pk_add_f32 v[44:45], v[44:45], 1.0 op_sel_hi:[1,0]
	s_nop 0
	v_rcp_f32_e32 v44, v44
	v_rcp_f32_e32 v45, v45
	s_nop 0
	v_pk_mul_f32 v[44:45], v[46:47], v[44:45]
	s_nop 0
	v_pk_mul_f32 v[42:43], v[44:45], v[42:43]
	v_pk_mul_f32 v[44:45], v[36:37], s[30:31] op_sel_hi:[1,0]
	s_nop 0
	v_exp_f32_e32 v44, v44
	v_exp_f32_e32 v45, v45
	s_nop 0
	v_pk_add_f32 v[44:45], v[44:45], 1.0 op_sel_hi:[1,0]
; DI unsigned pk2(float lo, float hi) { f32x2 v = {lo, hi}; return __builtin_bit_cast(unsigned, __builtin_convertvector(v, bf2_t)); }
; #define PG8_BAR __builtin_amdgcn_s_barrier()
; DI f32x2 swiglu_pk(f32x2 g, f32x2 u) {
;     const f32x2 t = g * (-1.44269504089f);
;     f32x2 e; e.x = __builtin_amdgcn_exp2f(t.x); e.y = __builtin_amdgcn_exp2f(t.y);
;     const f32x2 d = e + 1.0f;
;     f32x2 r; r.x = __builtin_amdgcn_rcpf(d.x); r.y = __builtin_amdgcn_rcpf(d.y);
;     return (g * r) * u;
; }
;     DI void operator()(const f32x4 (&acc)[2][2][4][2], const Unit& u, int wr, int wc, int fr, int fq) const {
;         const int row0 = u.pm * BM + wr * 64 + fr, col0 = u.pn * HALF + wc * 32 + 8 * fq;
; #pragma unroll
;         for (int ai = 0; ai < 2; ++ai)
; #pragma unroll
;             for (int m = 0; m < 4; ++m) {
;                 bf16_t* rowp = H + (size_t)(row0 + ai * HALF + m * 16) * ldh + col0;
;                 const f32x4 g0 = acc[ai][0][m][0], g1 = acc[ai][0][m][1], u0 = acc[ai][1][m][0], u1 = acc[ai][1][m][1];
;                 const f32x2 ha = swiglu_pk((f32x2){g0[0], g0[1]}, (f32x2){u0[0], u0[1]}), hb = swiglu_pk((f32x2){g0[2], g0[3]}, (f32x2){u0[2], u0[3]});
;                 const f32x2 hc = swiglu_pk((f32x2){g1[0], g1[1]}, (f32x2){u1[0], u1[1]}), hd = swiglu_pk((f32x2){g1[2], g1[3]}, (f32x2){u1[2], u1[3]});
;                 u32x4 w; w.x = pk2(ha.x, ha.y); w.y = pk2(hb.x, hb.y); w.z = pk2(hc.x, hc.y); w.w = pk2(hd.x, hd.y);
;                 *(u32x4*)rowp = w;
;             }
;     }
; template <class Epi, bool ALIGN_EPI, bool SP2, bool ROWHALF = false>
; DI void gemm_phase(LAS unsigned char* lds, const Gemm g, const StaticOrder& S, const Epi& E) {
;     ...
;         if constexpr (ALIGN_EPI) { if (wr == 0) PG8_BAR; }
;         if constexpr (!Epi::AFTER_DRAIN) E(acc, cur, wr, wc, fr, fq);
;         if (!has_next) break;
; #pragma unroll
;         for (int a = 0; a < 2; ++a)
; #pragma unroll
;             for (int b = 0; b < 2; ++b)
; #pragma unroll
;                 for (int m = 0; m < 4; ++m)
; #pragma unroll
;                     for (int n = 0; n < 2; ++n) acc[a][b][m][n] = (f32x4){0.f, 0.f, 0.f, 0.f};
;         cur = nxt; cA = nA; cB = nB; ++ui;
;         if constexpr (ALIGN_EPI) { if (wr == 1) PG8_BAR; }
	s_nop 0
	v_rcp_f32_e32 v44, v44
	v_rcp_f32_e32 v45, v45
	s_nop 0
	v_pk_mul_f32 v[36:37], v[36:37], v[44:45]
	s_nop 0
	v_pk_mul_f32 v[36:37], v[36:37], v[32:33]
	v_pk_mul_f32 v[32:33], v[38:39], s[30:31] op_sel_hi:[1,0]
	s_nop 0
	v_exp_f32_e32 v32, v32
	v_exp_f32_e32 v33, v33
	s_nop 0
	v_pk_add_f32 v[32:33], v[32:33], 1.0 op_sel_hi:[1,0]
	s_nop 0
	v_rcp_f32_e32 v32, v32
	v_rcp_f32_e32 v33, v33
	s_nop 0
	v_pk_mul_f32 v[32:33], v[38:39], v[32:33]
	s_nop 0
	v_pk_mul_f32 v[38:39], v[32:33], v[34:35]
	v_cvt_pk_bf16_f32 v32, v40, v41
	v_cvt_pk_bf16_f32 v33, v42, v43
	v_cvt_pk_bf16_f32 v34, v36, v37
	v_cvt_pk_bf16_f32 v35, v38, v39
	global_store_dwordx4 v[48:49], v[32:35], off sc1
	s_nop 1
	v_pk_mul_f32 v[34:35], v[28:29], s[30:31] op_sel_hi:[1,0]
	v_add_u32_e32 v32, 0xa0, v148
	v_exp_f32_e32 v34, v34
	v_exp_f32_e32 v35, v35
	v_mad_i64_i32 v[32:33], s[20:21], v32, s15, v[140:141]
	v_lshl_add_u64 v[32:33], v[32:33], 0, v[142:143]
	v_pk_add_f32 v[34:35], v[34:35], 1.0 op_sel_hi:[1,0]
	s_nop 0
	v_rcp_f32_e32 v34, v34
	v_rcp_f32_e32 v35, v35
	s_nop 0
	v_pk_mul_f32 v[28:29], v[28:29], v[34:35]
	s_nop 0
	v_pk_mul_f32 v[24:25], v[28:29], v[24:25]
	v_pk_mul_f32 v[28:29], v[30:31], s[30:31] op_sel_hi:[1,0]
	s_nop 0
	v_exp_f32_e32 v28, v28
	v_exp_f32_e32 v29, v29
	s_nop 0
	v_pk_add_f32 v[28:29], v[28:29], 1.0 op_sel_hi:[1,0]
	s_nop 0
	v_rcp_f32_e32 v28, v28
	v_rcp_f32_e32 v29, v29
	s_nop 0
	v_pk_mul_f32 v[28:29], v[30:31], v[28:29]
	s_nop 0
	v_pk_mul_f32 v[26:27], v[28:29], v[26:27]
	v_pk_mul_f32 v[28:29], v[20:21], s[30:31] op_sel_hi:[1,0]
	s_nop 0
	v_exp_f32_e32 v28, v28
	v_exp_f32_e32 v29, v29
	s_nop 0
	v_pk_add_f32 v[28:29], v[28:29], 1.0 op_sel_hi:[1,0]
	s_nop 0
	v_rcp_f32_e32 v28, v28
	v_rcp_f32_e32 v29, v29
	s_nop 0
	v_pk_mul_f32 v[20:21], v[20:21], v[28:29]
	s_nop 0
	v_pk_mul_f32 v[20:21], v[20:21], v[16:17]
	v_pk_mul_f32 v[16:17], v[22:23], s[30:31] op_sel_hi:[1,0]
	s_nop 0
	v_exp_f32_e32 v16, v16
	v_exp_f32_e32 v17, v17
	s_nop 0
	v_pk_add_f32 v[16:17], v[16:17], 1.0 op_sel_hi:[1,0]
	s_nop 0
	v_rcp_f32_e32 v16, v16
	v_rcp_f32_e32 v17, v17
	s_nop 0
	v_pk_mul_f32 v[16:17], v[22:23], v[16:17]
	s_nop 0
	v_pk_mul_f32 v[22:23], v[16:17], v[18:19]
	v_cvt_pk_bf16_f32 v16, v24, v25
	v_cvt_pk_bf16_f32 v17, v26, v27
	v_cvt_pk_bf16_f32 v18, v20, v21
	v_cvt_pk_bf16_f32 v19, v22, v23
	global_store_dwordx4 v[32:33], v[16:19], off sc1
	s_nop 1
	v_pk_mul_f32 v[18:19], v[12:13], s[30:31] op_sel_hi:[1,0]
	v_add_u32_e32 v16, 0xb0, v148
	v_exp_f32_e32 v18, v18
	v_exp_f32_e32 v19, v19
	v_mad_i64_i32 v[16:17], s[20:21], v16, s15, v[140:141]
	v_lshl_add_u64 v[16:17], v[16:17], 0, v[142:143]
	v_pk_add_f32 v[18:19], v[18:19], 1.0 op_sel_hi:[1,0]
	s_mov_b64 s[20:21], -1
	v_rcp_f32_e32 v18, v18
	v_rcp_f32_e32 v19, v19
	s_nop 0
	v_pk_mul_f32 v[12:13], v[12:13], v[18:19]
	s_nop 0
	v_pk_mul_f32 v[8:9], v[12:13], v[8:9]
	v_pk_mul_f32 v[12:13], v[14:15], s[30:31] op_sel_hi:[1,0]
	s_nop 0
	v_exp_f32_e32 v12, v12
	v_exp_f32_e32 v13, v13
	s_nop 0
	v_pk_add_f32 v[12:13], v[12:13], 1.0 op_sel_hi:[1,0]
	s_nop 0
	v_rcp_f32_e32 v12, v12
	v_rcp_f32_e32 v13, v13
	s_nop 0
	v_pk_mul_f32 v[12:13], v[14:15], v[12:13]
	s_nop 0
	v_pk_mul_f32 v[10:11], v[12:13], v[10:11]
	v_pk_mul_f32 v[12:13], v[4:5], s[30:31] op_sel_hi:[1,0]
	s_nop 0
	v_exp_f32_e32 v12, v12
	v_exp_f32_e32 v13, v13
	s_nop 0
	v_pk_add_f32 v[12:13], v[12:13], 1.0 op_sel_hi:[1,0]
	s_nop 0
	v_rcp_f32_e32 v12, v12
	v_rcp_f32_e32 v13, v13
	s_nop 0
	v_pk_mul_f32 v[4:5], v[4:5], v[12:13]
	s_nop 0
	v_pk_mul_f32 v[4:5], v[4:5], v[0:1]
	v_pk_mul_f32 v[0:1], v[6:7], s[30:31] op_sel_hi:[1,0]
	s_nop 0
	v_exp_f32_e32 v0, v0
	v_exp_f32_e32 v1, v1
	s_nop 0
	v_pk_add_f32 v[0:1], v[0:1], 1.0 op_sel_hi:[1,0]
	s_nop 0
	v_rcp_f32_e32 v0, v0
	v_rcp_f32_e32 v1, v1
	s_nop 0
	v_pk_mul_f32 v[0:1], v[6:7], v[0:1]
	s_nop 0
	v_pk_mul_f32 v[6:7], v[0:1], v[2:3]
	v_cvt_pk_bf16_f32 v0, v8, v9
	v_cvt_pk_bf16_f32 v1, v10, v11
	v_cvt_pk_bf16_f32 v2, v4, v5
	v_cvt_pk_bf16_f32 v3, v6, v7
	global_store_dwordx4 v[16:17], v[0:3], off sc1
	s_cbranch_vccnz .LBB0_236
	s_andn2_b64 vcc, exec, s[22:23]
	s_cbranch_vccnz .LBB0_235
	s_barrier
	s_branch .LBB0_235
